# code placement: K-loop heads at byte phases 20 / 32 / 12 mod 64
# speedup vs baseline: 1.0062x; 1.0014x over previous
;     ...
;         const bool has_next = S.next(ui + 1, nxt);
;         const char* nA = has_next ? nxt.A : cA; const char* nB = has_next ? nxt.B : cB;
;         for (int t = 0; t < nt; t += 2) {
;             const bool last = (t == nt - 2);
;             const char* a1 = cA + (size_t)(t + 1) * kstep;
;             const char* a2 = last ? nA : cA + (size_t)(t + 2) * kstep; const char* b2 = last ? nB : cB + (size_t)(t + 2) * kstep;
.LBB0_415:
	s_mov_b64 s[12:13], s[18:19]
	v_mov_b32_e32 v150, v144
	s_xor_b64 s[18:19], s[16:17], -1
	v_mov_b32_e32 v144, s13
	s_mov_b64 s[68:69], s[2:3]
	s_and_b64 s[0:1], s[16:17], exec
	v_cndmask_b32_e64 v151, v129, v144, s[16:17]
	v_mov_b32_e32 v144, s12
	s_mov_b64 s[56:57], s[8:9]
	s_mov_b32 s62, s26
	s_cselect_b32 s6, s69, s53
	s_cselect_b32 s7, s68, s52
	v_cndmask_b32_e64 v152, v128, v144, s[16:17]
	s_mov_b32 s2, 0
	s_mov_b64 s[0:1], 0x100
	v_mov_b64_e32 v[144:145], v[142:143]
	v_mov_b64_e32 v[146:147], v[140:141]
	s_nop 0
	s_nop 0
	s_nop 0
	s_nop 0
	s_nop 0
	s_nop 0
	s_nop 0
	s_nop 0
	s_nop 0
	s_nop 0
	s_nop 0
	s_nop 0
